# mix1a: each block runs its long-window poolc tile before its short-window one and every block ends the phase with a kvstate tile (second co-resident block: kvstate, poolc, poolc, kvstate)
# baseline (speedup 1.0000x reference)
.LBB0_500:
	s_or_b64 exec, exec, s[0:1]
	s_cmpk_gt_i32 s2, 0x7ff
	s_waitcnt lgkmcnt(0)
	s_barrier
	s_cbranch_scc1 .LBB0_515
	v_xor_b32_e32 v1, v128, v131
	v_lshlrev_b32_e32 v1, 3, v1
	s_movk_i32 s1, 0x1e0
	v_and_b32_e32 v2, 56, v1
	v_and_b32_e32 v1, 0x60, v158
	v_and_or_b32 v4, v153, s1, v138
	v_bitop3_b32 v6, v128, v139, 3 bitop3:0x6c
	s_movk_i32 s0, 0x60
	v_lshlrev_b32_e32 v7, 4, v6
	v_lshlrev_b32_e32 v9, 7, v4
	v_lshlrev_b32_e32 v4, 7, v1
	v_and_b32_e32 v6, 0x1f0, v153
	s_movk_i32 s1, 0x50
	v_bitop3_b32 v24, v4, v6, s0 bitop3:0xf6
	s_movk_i32 s0, 0x70
	v_or_b32_e32 v13, v4, v6
	v_bitop3_b32 v15, v4, v6, 16 bitop3:0xf6
	v_bitop3_b32 v17, v4, v6, 32 bitop3:0xf6
	v_bitop3_b32 v19, v4, v6, 48 bitop3:0xf6
	v_bitop3_b32 v22, v4, v6, 64 bitop3:0xf6
	v_bitop3_b32 v23, v4, v6, s1 bitop3:0xf6
	v_bitop3_b32 v25, v4, v6, s0 bitop3:0xf6
	v_lshlrev_b32_e32 v10, 13, v135
	v_lshl_add_u32 v4, v134, 3, v138
	v_lshlrev_b32_e32 v8, 5, v138
	v_or3_b32 v67, v10, v137, v8
	v_add_u32_e32 v8, 0x60, v4
	v_lshl_or_b32 v6, v134, 11, v10
	v_and_b32_e32 v8, 0x7f, v8
	v_lshl_or_b32 v148, v4, 2, v6
	v_lshl_or_b32 v149, v8, 2, v6
	v_add_u32_e32 v4, 0x70, v4
	v_add_u32_e32 v8, 8, v133
	v_lshlrev_b32_e32 v12, 5, v135
	v_and_b32_e32 v4, 0x7f, v4
	v_and_b32_e32 v8, 0x78, v8
	v_mov_b32_e32 v65, 0
	v_lshl_or_b32 v150, v4, 2, v6
	v_or_b32_e32 v20, v134, v12
	v_lshlrev_b32_e32 v6, 9, v136
	v_lshlrev_b32_e32 v8, 2, v8
	v_or_b32_e32 v21, v136, v12
	v_add_u32_e32 v14, 16, v133
	v_lshlrev_b32_e32 v64, 1, v1
	v_lshlrev_b32_e32 v4, 7, v20
	v_or3_b32 v151, v10, v6, v8
	v_lshlrev_b32_e32 v6, 7, v21
	v_and_b32_e32 v14, 0x78, v14
	v_add_u32_e32 v16, 24, v133
	v_lshlrev_b32_e32 v68, 12, v20
	v_lshlrev_b32_e32 v70, 12, v21
	v_lshl_add_u64 v[20:21], s[50:51], 0, v[64:65]
	s_mov_b64 s[0:1], 0xba00000
	v_lshlrev_b32_e32 v64, 9, v157
	v_lshlrev_b32_e32 v8, 9, v132
	v_lshlrev_b32_e32 v14, 2, v14
	v_and_b32_e32 v16, 0x78, v16
	v_or_b32_e32 v18, 16, v12
	v_lshl_add_u64 v[84:85], v[20:21], 0, s[0:1]
	v_lshl_add_u64 v[20:21], s[50:51], 0, v[64:65]
	v_lshlrev_b32_e32 v64, 1, v2
	v_or3_b32 v160, v10, v8, v14
	v_or_b32_e32 v26, v132, v12
	v_lshlrev_b32_e32 v14, 9, v130
	v_lshlrev_b32_e32 v16, 2, v16
	v_or_b32_e32 v27, v130, v12
	v_or_b32_e32 v28, v18, v134
	v_or_b32_e32 v29, v136, v18
	v_or_b32_e32 v30, v132, v18
	v_or_b32_e32 v31, v130, v18
	v_lshl_add_u64 v[20:21], v[20:21], 0, v[64:65]
	s_mov_b64 s[0:1], 0x1000000
	v_and_b32_e32 v0, 0x7f000, v156
	v_and_b32_e32 v3, 14, v153
	v_lshlrev_b32_e32 v5, 7, v138
	v_lshlrev_b32_e32 v11, 4, v152
	v_lshlrev_b32_e32 v8, 7, v26
	v_or3_b32 v161, v10, v14, v16
	v_lshlrev_b32_e32 v10, 7, v27
	v_lshlrev_b32_e32 v12, 7, v28
	v_lshlrev_b32_e32 v14, 7, v29
	v_lshlrev_b32_e32 v16, 7, v30
	v_lshlrev_b32_e32 v18, 7, v31
	s_add_u32 s33, s50, 0x3a00000
	v_lshl_add_u64 v[86:87], v[20:21], 0, s[0:1]
	v_lshl_add_u64 v[20:21], s[50:51], 0, v[64:65]
	s_mov_b64 s[0:1], 0x1a00000
	v_lshlrev_b32_e32 v66, 3, v138
	v_and_b32_e32 v162, 0x70, v129
	v_mov_b32_e32 v69, v65
	v_mov_b32_e32 v71, v65
	v_lshlrev_b32_e32 v72, 12, v26
	v_mov_b32_e32 v73, v65
	v_lshlrev_b32_e32 v74, 12, v27
	v_mov_b32_e32 v75, v65
	v_lshlrev_b32_e32 v76, 12, v28
	v_mov_b32_e32 v77, v65
	v_lshlrev_b32_e32 v78, 12, v29
	v_mov_b32_e32 v79, v65
	v_lshlrev_b32_e32 v80, 12, v30
	v_mov_b32_e32 v81, v65
	v_lshlrev_b32_e32 v82, 12, v31
	v_mov_b32_e32 v83, v65
	s_addc_u32 s44, s51, 0
	v_lshl_add_u64 v[88:89], v[20:21], 0, s[0:1]
	s_mov_b32 s45, 0xc2fc0000
	s_mov_b32 s46, 0x3f2aaaab
	v_mov_b32_e32 v163, 0x3ecc95a3
	s_mov_b32 s47, 0x3f317218
	s_mov_b32 s52, 0x33800000
	s_mov_b32 s19, 0
	v_lshlrev_b32_e32 v90, 1, v0
	v_lshlrev_b32_e32 v92, 1, v2
	s_mov_b64 s[20:21], 0x40000
	v_add_u32_e32 v164, 0x1000, v129
	s_mov_b64 s[22:23], 0x80000
	v_add_u32_e32 v165, 0x2000, v129
	s_mov_b64 s[24:25], 0xc0000
	v_add_u32_e32 v166, 0x3000, v129
	s_movk_i32 s53, 0x7fff
	v_add_u32_e32 v167, v13, v3
	v_add_u32_e32 v168, v15, v3
	v_add_u32_e32 v169, v17, v3
	v_add_u32_e32 v170, v19, v3
	v_add_u32_e32 v171, v22, v3
	v_add_u32_e32 v172, v23, v3
	v_add_u32_e32 v173, v24, v3
	v_add_u32_e32 v174, v25, v3
	v_add_u32_e32 v175, v7, v9
	v_add_u32_e32 v176, v7, v5
	v_add_u32_e32 v177, v11, v9
	v_add_u32_e32 v178, v11, v5
	s_mov_b32 s54, 0x7060302
	v_lshlrev_b32_e32 v94, 1, v4
	v_lshlrev_b32_e32 v96, 1, v6
	v_lshlrev_b32_e32 v98, 1, v8
	v_lshlrev_b32_e32 v100, 1, v10
	v_lshlrev_b32_e32 v102, 1, v12
	v_lshlrev_b32_e32 v104, 1, v14
	v_lshlrev_b32_e32 v106, 1, v16
	v_lshlrev_b32_e32 v108, 1, v18
	s_mov_b64 s[26:27], 0x4000
	s_mov_b64 s[28:29], 0x8000
	s_mov_b64 s[30:31], 0xc000
	s_mov_b64 s[34:35], 0x10000
	s_movk_i32 s55, 0xf800
	v_mov_b32_e32 v179, 0x42800000
	v_mov_b32_e32 v180, 0x7fc00000
	v_mov_b32_e32 v181, 0xff800000
	s_mov_b32 s56, s2
	s_mov_b32 s99, 0
	s_cmp_eq_u32 s3, 0x200
	s_cbranch_scc0 .Lmy_m1a_gen
	s_mov_b32 s99, 1
	s_bfe_u32 s61, s2, 0x20001
	s_add_i32 s62, s2, 0x200
	s_cmp_ge_u32 s61, 2
	s_cselect_b32 s63, s2, s62
	s_cselect_b32 s64, s62, s2
	s_add_i32 s65, s2, 0x400
	s_add_i32 s66, s2, 0x600
	s_and_b32 s67, s2, 0x100
	s_cmp_eq_u32 s67, 0
	s_cselect_b32 s68, s63, s65
	s_cselect_b32 s69, s64, s63
	s_cselect_b32 s70, s65, s64
	s_mov_b32 s71, s66
	s_mov_b32 s60, 0
	s_mov_b32 s56, s68

.LBB0_502:
	s_cmp_eq_u32 s99, 0
	s_cbranch_scc1 .Lmy_m1a_stride
	s_add_i32 s60, s60, 1
	s_cmp_eq_u32 s60, 1
	s_cselect_b32 s56, s69, -1
	s_cmp_eq_u32 s60, 2
	s_cselect_b32 s56, s70, s56
	s_cmp_eq_u32 s60, 3
	s_cselect_b32 s56, s71, s56
	s_cmp_lt_i32 s56, 0
	s_cbranch_scc1 .LBB0_515
	s_branch .LBB0_503
